# grid barrier: non-leader workgroups poll the top-level generation word directly instead of their XCD generation word (one hop less on the release path); otherwise v5
# baseline (speedup 1.0000x reference)
; __device__ __forceinline__ unsigned xb_ld(unsigned* p)              { return __hip_atomic_load(p, __ATOMIC_RELAXED, __HIP_MEMORY_SCOPE_AGENT); }
; __device__ __forceinline__ unsigned xb_add(unsigned* p, unsigned v) { return __hip_atomic_fetch_add(p, v, __ATOMIC_RELAXED, __HIP_MEMORY_SCOPE_AGENT); }
; #define XB_SPIN(cond, bar) do { unsigned _sp = 0; while (cond) { __builtin_amdgcn_s_sleep(1); \
;     if ((++_sp & 255u) == 0u) { if (xb_ld(&(bar)[XB_TMO])) break; if (_sp > XB_SPIN_CAP) { atomicAdd(&(bar)[XB_TMO], 1u); break; } } } } while (0)
; __device__ __forceinline__ void xcd_barrier(const XcdBarrier& b) {
;     ...
;         const unsigned old = xb_add(&bar[XB_XSUB(b.x)], 1u);
;         const unsigned gen = old / nloc;
;         if (old + 1u == (gen + 1u) * nloc) {
;             __builtin_amdgcn_fence(__ATOMIC_RELEASE, "agent");
;             asm volatile("s_waitcnt vmcnt(0)" ::: "memory");
;             const unsigned og = xb_add(&bar[XB_TOP], 1u);
;             const unsigned tg = og / nx;
;             if (og + 1u == (tg + 1u) * nx) xb_add(&bar[XB_TOPGEN], 1u);
;             else XB_SPIN(xb_ld(&bar[XB_TOPGEN]) == tg, bar);
;             __builtin_amdgcn_fence(__ATOMIC_ACQUIRE, "agent");
;             xb_add(&bar[XB_XGEN(b.x)], 1u);
;             asm volatile("s_waitcnt vmcnt(0)" ::: "memory");
;         } else {
;             XB_SPIN(xb_ld(&bar[XB_XGEN(b.x)]) == gen, bar);
.LBB0_137:
	s_or_b64 exec, exec, s[8:9]
	v_cvt_f32_u32_e32 v4, v2
	s_waitcnt vmcnt(0)
	v_readfirstlane_b32 s6, v3
	v_sub_u32_e32 v3, 0, v2
	v_rcp_iflag_f32_e32 v4, v4
	v_add_u32_e32 v5, s6, v1
	v_mul_f32_e32 v4, 0x4f7ffffe, v4
	v_cvt_u32_f32_e32 v4, v4
	v_mul_lo_u32 v1, v3, v4
	v_mul_hi_u32 v1, v4, v1
	v_add_u32_e32 v1, v4, v1
	v_mul_hi_u32 v1, v5, v1
	v_mul_lo_u32 v3, v1, v2
	v_sub_u32_e32 v3, v5, v3
	v_add_u32_e32 v4, 1, v1
	v_cmp_ge_u32_e32 vcc, v3, v2
	s_nop 1
	v_cndmask_b32_e32 v1, v1, v4, vcc
	v_sub_u32_e32 v4, v3, v2
	v_cndmask_b32_e32 v3, v3, v4, vcc
	v_add_u32_e32 v4, 1, v1
	v_cmp_ge_u32_e32 vcc, v3, v2
	v_add_u32_e32 v3, 1, v5
	s_nop 0
	v_cndmask_b32_e32 v1, v1, v4, vcc
	v_mul_lo_u32 v4, v2, v1
	v_add_u32_e32 v2, v4, v2
	v_cmp_ne_u32_e32 vcc, v3, v2
	s_and_saveexec_b64 s[6:7], vcc
	s_xor_b64 s[6:7], exec, s[6:7]
	s_cbranch_execz .LBB0_151
	s_waitcnt lgkmcnt(0)
	v_mov_b32_e32 v0, 0x3100
	global_load_dword v0, v0, s[34:35] offset:1024 sc1
	s_add_u32 s10, s34, 0x3500
	s_addc_u32 s11, s35, 0
	s_waitcnt vmcnt(0)
	v_cmp_eq_u32_e32 vcc, v0, v1
	s_and_saveexec_b64 s[8:9], vcc
	s_cbranch_execz .LBB0_150
	s_mov_b32 s37, 1
	s_mov_b64 s[16:17], 0
	v_mov_b32_e32 v0, 0
	s_branch .LBB0_141

; __device__ __forceinline__ unsigned xb_ld(unsigned* p)              { return __hip_atomic_load(p, __ATOMIC_RELAXED, __HIP_MEMORY_SCOPE_AGENT); }
; __device__ __forceinline__ unsigned xb_add(unsigned* p, unsigned v) { return __hip_atomic_fetch_add(p, v, __ATOMIC_RELAXED, __HIP_MEMORY_SCOPE_AGENT); }
; #define XB_SPIN(cond, bar) do { unsigned _sp = 0; while (cond) { __builtin_amdgcn_s_sleep(1); \
;     if ((++_sp & 255u) == 0u) { if (xb_ld(&(bar)[XB_TMO])) break; if (_sp > XB_SPIN_CAP) { atomicAdd(&(bar)[XB_TMO], 1u); break; } } } } while (0)
; __device__ __forceinline__ void xcd_barrier(const XcdBarrier& b) {
;     ...
;         const unsigned old = xb_add(&bar[XB_XSUB(b.x)], 1u);
;         const unsigned gen = old / nloc;
;         if (old + 1u == (gen + 1u) * nloc) {
;             __builtin_amdgcn_fence(__ATOMIC_RELEASE, "agent");
;             asm volatile("s_waitcnt vmcnt(0)" ::: "memory");
;             const unsigned og = xb_add(&bar[XB_TOP], 1u);
;             const unsigned tg = og / nx;
;             if (og + 1u == (tg + 1u) * nx) xb_add(&bar[XB_TOPGEN], 1u);
;             else XB_SPIN(xb_ld(&bar[XB_TOPGEN]) == tg, bar);
;             __builtin_amdgcn_fence(__ATOMIC_ACQUIRE, "agent");
;             xb_add(&bar[XB_XGEN(b.x)], 1u);
;             asm volatile("s_waitcnt vmcnt(0)" ::: "memory");
;         } else {
;             XB_SPIN(xb_ld(&bar[XB_XGEN(b.x)]) == gen, bar);
.LBB0_240:
	s_or_b64 exec, exec, s[8:9]
	v_cvt_f32_u32_e32 v4, v2
	s_waitcnt vmcnt(0)
	v_readfirstlane_b32 s6, v3
	v_sub_u32_e32 v3, 0, v2
	v_rcp_iflag_f32_e32 v4, v4
	v_add_u32_e32 v5, s6, v1
	v_mul_f32_e32 v4, 0x4f7ffffe, v4
	v_cvt_u32_f32_e32 v4, v4
	v_mul_lo_u32 v1, v3, v4
	v_mul_hi_u32 v1, v4, v1
	v_add_u32_e32 v1, v4, v1
	v_mul_hi_u32 v1, v5, v1
	v_mul_lo_u32 v3, v1, v2
	v_sub_u32_e32 v3, v5, v3
	v_add_u32_e32 v4, 1, v1
	v_cmp_ge_u32_e32 vcc, v3, v2
	s_nop 1
	v_cndmask_b32_e32 v1, v1, v4, vcc
	v_sub_u32_e32 v4, v3, v2
	v_cndmask_b32_e32 v3, v3, v4, vcc
	v_add_u32_e32 v4, 1, v1
	v_cmp_ge_u32_e32 vcc, v3, v2
	v_add_u32_e32 v3, 1, v5
	s_nop 0
	v_cndmask_b32_e32 v1, v1, v4, vcc
	v_mul_lo_u32 v4, v2, v1
	v_add_u32_e32 v2, v4, v2
	v_cmp_ne_u32_e32 vcc, v3, v2
	s_and_saveexec_b64 s[6:7], vcc
	s_xor_b64 s[6:7], exec, s[6:7]
	s_cbranch_execz .LBB0_254
	s_waitcnt lgkmcnt(0)
	v_mov_b32_e32 v0, 0x3100
	global_load_dword v0, v0, s[34:35] offset:1024 sc1
	s_add_u32 s10, s34, 0x3500
	s_addc_u32 s11, s35, 0
	s_waitcnt vmcnt(0)
	v_cmp_eq_u32_e32 vcc, v0, v1
	s_and_saveexec_b64 s[8:9], vcc
	s_cbranch_execz .LBB0_253
	s_mov_b32 s20, 1
	s_mov_b64 s[12:13], 0
	v_mov_b32_e32 v0, 0
	s_branch .LBB0_244

; __device__ __forceinline__ unsigned xb_ld(unsigned* p)              { return __hip_atomic_load(p, __ATOMIC_RELAXED, __HIP_MEMORY_SCOPE_AGENT); }
; __device__ __forceinline__ unsigned xb_add(unsigned* p, unsigned v) { return __hip_atomic_fetch_add(p, v, __ATOMIC_RELAXED, __HIP_MEMORY_SCOPE_AGENT); }
; #define XB_SPIN(cond, bar) do { unsigned _sp = 0; while (cond) { __builtin_amdgcn_s_sleep(1); \
;     if ((++_sp & 255u) == 0u) { if (xb_ld(&(bar)[XB_TMO])) break; if (_sp > XB_SPIN_CAP) { atomicAdd(&(bar)[XB_TMO], 1u); break; } } } } while (0)
; __device__ __forceinline__ void xcd_barrier(const XcdBarrier& b) {
;     ...
;         const unsigned old = xb_add(&bar[XB_XSUB(b.x)], 1u);
;         const unsigned gen = old / nloc;
;         if (old + 1u == (gen + 1u) * nloc) {
;             __builtin_amdgcn_fence(__ATOMIC_RELEASE, "agent");
;             asm volatile("s_waitcnt vmcnt(0)" ::: "memory");
;             const unsigned og = xb_add(&bar[XB_TOP], 1u);
;             const unsigned tg = og / nx;
;             if (og + 1u == (tg + 1u) * nx) xb_add(&bar[XB_TOPGEN], 1u);
;             else XB_SPIN(xb_ld(&bar[XB_TOPGEN]) == tg, bar);
;             __builtin_amdgcn_fence(__ATOMIC_ACQUIRE, "agent");
;             xb_add(&bar[XB_XGEN(b.x)], 1u);
;             asm volatile("s_waitcnt vmcnt(0)" ::: "memory");
;         } else {
;             XB_SPIN(xb_ld(&bar[XB_XGEN(b.x)]) == gen, bar);
.LBB0_336:
	s_or_b64 exec, exec, s[10:11]
	v_cvt_f32_u32_e32 v4, v2
	s_waitcnt vmcnt(0)
	v_readfirstlane_b32 s0, v3
	v_sub_u32_e32 v3, 0, v2
	v_rcp_iflag_f32_e32 v4, v4
	v_add_u32_e32 v5, s0, v1
	v_mul_f32_e32 v4, 0x4f7ffffe, v4
	v_cvt_u32_f32_e32 v4, v4
	v_mul_lo_u32 v1, v3, v4
	v_mul_hi_u32 v1, v4, v1
	v_add_u32_e32 v1, v4, v1
	v_mul_hi_u32 v1, v5, v1
	v_mul_lo_u32 v3, v1, v2
	v_sub_u32_e32 v3, v5, v3
	v_add_u32_e32 v4, 1, v1
	v_cmp_ge_u32_e32 vcc, v3, v2
	s_nop 1
	v_cndmask_b32_e32 v1, v1, v4, vcc
	v_sub_u32_e32 v4, v3, v2
	v_cndmask_b32_e32 v3, v3, v4, vcc
	v_add_u32_e32 v4, 1, v1
	v_cmp_ge_u32_e32 vcc, v3, v2
	v_add_u32_e32 v3, 1, v5
	s_nop 0
	v_cndmask_b32_e32 v1, v1, v4, vcc
	v_mul_lo_u32 v4, v2, v1
	v_add_u32_e32 v2, v4, v2
	v_cmp_ne_u32_e32 vcc, v3, v2
	s_and_saveexec_b64 s[0:1], vcc
	s_xor_b64 s[8:9], exec, s[0:1]
	s_cbranch_execz .LBB0_350
	s_waitcnt lgkmcnt(0)
	v_mov_b32_e32 v0, 0x3100
	global_load_dword v0, v0, s[34:35] offset:1024 sc1
	s_add_u32 s12, s34, 0x3500
	s_addc_u32 s13, s35, 0
	s_waitcnt vmcnt(0)
	v_cmp_eq_u32_e32 vcc, v0, v1
	s_and_saveexec_b64 s[10:11], vcc
	s_cbranch_execz .LBB0_349
	s_mov_b32 s0, 1
	s_mov_b64 s[16:17], 0
	v_mov_b32_e32 v0, 0
	s_branch .LBB0_340

; __device__ __forceinline__ unsigned xb_ld(unsigned* p)              { return __hip_atomic_load(p, __ATOMIC_RELAXED, __HIP_MEMORY_SCOPE_AGENT); }
; __device__ __forceinline__ unsigned xb_add(unsigned* p, unsigned v) { return __hip_atomic_fetch_add(p, v, __ATOMIC_RELAXED, __HIP_MEMORY_SCOPE_AGENT); }
; #define XB_SPIN(cond, bar) do { unsigned _sp = 0; while (cond) { __builtin_amdgcn_s_sleep(1); \
;     if ((++_sp & 255u) == 0u) { if (xb_ld(&(bar)[XB_TMO])) break; if (_sp > XB_SPIN_CAP) { atomicAdd(&(bar)[XB_TMO], 1u); break; } } } } while (0)
; __device__ __forceinline__ void xcd_barrier(const XcdBarrier& b) {
;     ...
;         const unsigned old = xb_add(&bar[XB_XSUB(b.x)], 1u);
;         const unsigned gen = old / nloc;
;         if (old + 1u == (gen + 1u) * nloc) {
;             __builtin_amdgcn_fence(__ATOMIC_RELEASE, "agent");
;             asm volatile("s_waitcnt vmcnt(0)" ::: "memory");
;             const unsigned og = xb_add(&bar[XB_TOP], 1u);
;             const unsigned tg = og / nx;
;             if (og + 1u == (tg + 1u) * nx) xb_add(&bar[XB_TOPGEN], 1u);
;             else XB_SPIN(xb_ld(&bar[XB_TOPGEN]) == tg, bar);
;             __builtin_amdgcn_fence(__ATOMIC_ACQUIRE, "agent");
;             xb_add(&bar[XB_XGEN(b.x)], 1u);
;             asm volatile("s_waitcnt vmcnt(0)" ::: "memory");
;         } else {
;             XB_SPIN(xb_ld(&bar[XB_XGEN(b.x)]) == gen, bar);
.LBB0_724:
	s_or_b64 exec, exec, s[10:11]
	v_cvt_f32_u32_e32 v4, v2
	s_waitcnt vmcnt(0)
	v_readfirstlane_b32 s0, v3
	v_sub_u32_e32 v3, 0, v2
	v_rcp_iflag_f32_e32 v4, v4
	v_add_u32_e32 v5, s0, v1
	v_mul_f32_e32 v4, 0x4f7ffffe, v4
	v_cvt_u32_f32_e32 v4, v4
	v_mul_lo_u32 v1, v3, v4
	v_mul_hi_u32 v1, v4, v1
	v_add_u32_e32 v1, v4, v1
	v_mul_hi_u32 v1, v5, v1
	v_mul_lo_u32 v3, v1, v2
	v_sub_u32_e32 v3, v5, v3
	v_add_u32_e32 v4, 1, v1
	v_cmp_ge_u32_e32 vcc, v3, v2
	s_nop 1
	v_cndmask_b32_e32 v1, v1, v4, vcc
	v_sub_u32_e32 v4, v3, v2
	v_cndmask_b32_e32 v3, v3, v4, vcc
	v_add_u32_e32 v4, 1, v1
	v_cmp_ge_u32_e32 vcc, v3, v2
	v_add_u32_e32 v3, 1, v5
	s_nop 0
	v_cndmask_b32_e32 v1, v1, v4, vcc
	v_mul_lo_u32 v4, v2, v1
	v_add_u32_e32 v2, v4, v2
	v_cmp_ne_u32_e32 vcc, v3, v2
	s_and_saveexec_b64 s[0:1], vcc
	s_xor_b64 s[8:9], exec, s[0:1]
	s_cbranch_execz .LBB0_738
	s_waitcnt lgkmcnt(0)
	v_mov_b32_e32 v0, 0x3100
	global_load_dword v0, v0, s[34:35] offset:1024 sc1
	s_add_u32 s12, s34, 0x3500
	s_addc_u32 s13, s35, 0
	s_waitcnt vmcnt(0)
	v_cmp_eq_u32_e32 vcc, v0, v1
	s_and_saveexec_b64 s[10:11], vcc
	s_cbranch_execz .LBB0_737
	s_mov_b32 s0, 1
	s_mov_b64 s[14:15], 0
	v_mov_b32_e32 v0, 0
	s_branch .LBB0_728

; __device__ __forceinline__ unsigned xb_ld(unsigned* p)              { return __hip_atomic_load(p, __ATOMIC_RELAXED, __HIP_MEMORY_SCOPE_AGENT); }
; __device__ __forceinline__ unsigned xb_add(unsigned* p, unsigned v) { return __hip_atomic_fetch_add(p, v, __ATOMIC_RELAXED, __HIP_MEMORY_SCOPE_AGENT); }
; #define XB_SPIN(cond, bar) do { unsigned _sp = 0; while (cond) { __builtin_amdgcn_s_sleep(1); \
;     if ((++_sp & 255u) == 0u) { if (xb_ld(&(bar)[XB_TMO])) break; if (_sp > XB_SPIN_CAP) { atomicAdd(&(bar)[XB_TMO], 1u); break; } } } } while (0)
; __device__ __forceinline__ void xcd_barrier(const XcdBarrier& b) {
;     ...
;         const unsigned old = xb_add(&bar[XB_XSUB(b.x)], 1u);
;         const unsigned gen = old / nloc;
;         if (old + 1u == (gen + 1u) * nloc) {
;             __builtin_amdgcn_fence(__ATOMIC_RELEASE, "agent");
;             asm volatile("s_waitcnt vmcnt(0)" ::: "memory");
;             const unsigned og = xb_add(&bar[XB_TOP], 1u);
;             const unsigned tg = og / nx;
;             if (og + 1u == (tg + 1u) * nx) xb_add(&bar[XB_TOPGEN], 1u);
;             else XB_SPIN(xb_ld(&bar[XB_TOPGEN]) == tg, bar);
;             __builtin_amdgcn_fence(__ATOMIC_ACQUIRE, "agent");
;             xb_add(&bar[XB_XGEN(b.x)], 1u);
;             asm volatile("s_waitcnt vmcnt(0)" ::: "memory");
;         } else {
;             XB_SPIN(xb_ld(&bar[XB_XGEN(b.x)]) == gen, bar);
.LBB0_810:
	s_or_b64 exec, exec, s[12:13]
	v_cvt_f32_u32_e32 v4, v2
	s_waitcnt vmcnt(0)
	v_readfirstlane_b32 s0, v3
	v_sub_u32_e32 v3, 0, v2
	v_rcp_iflag_f32_e32 v4, v4
	v_add_u32_e32 v5, s0, v1
	v_mul_f32_e32 v4, 0x4f7ffffe, v4
	v_cvt_u32_f32_e32 v4, v4
	v_mul_lo_u32 v1, v3, v4
	v_mul_hi_u32 v1, v4, v1
	v_add_u32_e32 v1, v4, v1
	v_mul_hi_u32 v1, v5, v1
	v_mul_lo_u32 v3, v1, v2
	v_sub_u32_e32 v3, v5, v3
	v_add_u32_e32 v4, 1, v1
	v_cmp_ge_u32_e32 vcc, v3, v2
	s_nop 1
	v_cndmask_b32_e32 v1, v1, v4, vcc
	v_sub_u32_e32 v4, v3, v2
	v_cndmask_b32_e32 v3, v3, v4, vcc
	v_add_u32_e32 v4, 1, v1
	v_cmp_ge_u32_e32 vcc, v3, v2
	v_add_u32_e32 v3, 1, v5
	s_nop 0
	v_cndmask_b32_e32 v1, v1, v4, vcc
	v_mul_lo_u32 v4, v2, v1
	v_add_u32_e32 v2, v4, v2
	v_cmp_ne_u32_e32 vcc, v3, v2
	s_and_saveexec_b64 s[0:1], vcc
	s_xor_b64 s[10:11], exec, s[0:1]
	s_cbranch_execz .LBB0_824
	s_waitcnt lgkmcnt(0)
	v_mov_b32_e32 v0, 0x3100
	global_load_dword v0, v0, s[34:35] offset:1024 sc1
	s_add_u32 s14, s34, 0x3500
	s_addc_u32 s15, s35, 0
	s_waitcnt vmcnt(0)
	v_cmp_eq_u32_e32 vcc, v0, v1
	s_and_saveexec_b64 s[12:13], vcc
	s_cbranch_execz .LBB0_823
	s_mov_b32 s0, 1
	s_mov_b64 s[16:17], 0
	v_mov_b32_e32 v0, 0
	s_branch .LBB0_814

; __device__ __forceinline__ unsigned xb_ld(unsigned* p)              { return __hip_atomic_load(p, __ATOMIC_RELAXED, __HIP_MEMORY_SCOPE_AGENT); }
; __device__ __forceinline__ unsigned xb_add(unsigned* p, unsigned v) { return __hip_atomic_fetch_add(p, v, __ATOMIC_RELAXED, __HIP_MEMORY_SCOPE_AGENT); }
; #define XB_SPIN(cond, bar) do { unsigned _sp = 0; while (cond) { __builtin_amdgcn_s_sleep(1); \
;     if ((++_sp & 255u) == 0u) { if (xb_ld(&(bar)[XB_TMO])) break; if (_sp > XB_SPIN_CAP) { atomicAdd(&(bar)[XB_TMO], 1u); break; } } } } while (0)
; __device__ __forceinline__ void xcd_barrier(const XcdBarrier& b) {
;     ...
;         const unsigned old = xb_add(&bar[XB_XSUB(b.x)], 1u);
;         const unsigned gen = old / nloc;
;         if (old + 1u == (gen + 1u) * nloc) {
;             __builtin_amdgcn_fence(__ATOMIC_RELEASE, "agent");
;             asm volatile("s_waitcnt vmcnt(0)" ::: "memory");
;             const unsigned og = xb_add(&bar[XB_TOP], 1u);
;             const unsigned tg = og / nx;
;             if (og + 1u == (tg + 1u) * nx) xb_add(&bar[XB_TOPGEN], 1u);
;             else XB_SPIN(xb_ld(&bar[XB_TOPGEN]) == tg, bar);
;             __builtin_amdgcn_fence(__ATOMIC_ACQUIRE, "agent");
;             xb_add(&bar[XB_XGEN(b.x)], 1u);
;             asm volatile("s_waitcnt vmcnt(0)" ::: "memory");
;         } else {
;             XB_SPIN(xb_ld(&bar[XB_XGEN(b.x)]) == gen, bar);
.LBB0_1633:
	s_or_b64 exec, exec, s[8:9]
	v_cvt_f32_u32_e32 v4, v2
	s_waitcnt vmcnt(0)
	v_readfirstlane_b32 s2, v3
	v_sub_u32_e32 v3, 0, v2
	v_rcp_iflag_f32_e32 v4, v4
	v_add_u32_e32 v5, s2, v1
	v_mul_f32_e32 v4, 0x4f7ffffe, v4
	v_cvt_u32_f32_e32 v4, v4
	v_mul_lo_u32 v1, v3, v4
	v_mul_hi_u32 v1, v4, v1
	v_add_u32_e32 v1, v4, v1
	v_mul_hi_u32 v1, v5, v1
	v_mul_lo_u32 v3, v1, v2
	v_sub_u32_e32 v3, v5, v3
	v_add_u32_e32 v4, 1, v1
	v_cmp_ge_u32_e32 vcc, v3, v2
	s_nop 1
	v_cndmask_b32_e32 v1, v1, v4, vcc
	v_sub_u32_e32 v4, v3, v2
	v_cndmask_b32_e32 v3, v3, v4, vcc
	v_add_u32_e32 v4, 1, v1
	v_cmp_ge_u32_e32 vcc, v3, v2
	v_add_u32_e32 v3, 1, v5
	s_nop 0
	v_cndmask_b32_e32 v1, v1, v4, vcc
	v_mul_lo_u32 v4, v2, v1
	v_add_u32_e32 v2, v4, v2
	v_cmp_ne_u32_e32 vcc, v3, v2
	s_and_saveexec_b64 s[2:3], vcc
	s_xor_b64 s[6:7], exec, s[2:3]
	s_cbranch_execz .LBB0_1647
	s_waitcnt lgkmcnt(0)
	v_mov_b32_e32 v0, 0x3100
	global_load_dword v0, v0, s[34:35] offset:1024 sc1
	s_add_u32 s10, s34, 0x3500
	s_addc_u32 s11, s35, 0
	s_waitcnt vmcnt(0)
	v_cmp_eq_u32_e32 vcc, v0, v1
	s_and_saveexec_b64 s[8:9], vcc
	s_cbranch_execz .LBB0_1646
	s_mov_b32 s2, 1
	s_mov_b64 s[12:13], 0
	v_mov_b32_e32 v0, 0
	s_branch .LBB0_1637
